# v27: v25 + conformer conv staging waits per row group (counted vmcnt) instead of one vmcnt(0) for all 16 row loads
# speedup vs baseline: 1.0081x; 1.0081x over previous
; #define LAS __attribute__((address_space(3)))
; __device__ __forceinline__ float sigm(float x) { return __builtin_amdgcn_rcpf(1.f + __builtin_amdgcn_exp2f(-1.44269504f * x)); }
; __device__ __forceinline__ void conv_unit_p(const bf16* __restrict__ Z, bf16* __restrict__ CAT, float* __restrict__ newc, ...
;     ...
;       for (int j = 0; j < 8; ++j) { const int r = 8 * j + rr, sx = t0 - 30 + r; const bool ok = (sx >= 0 && r < 62);
;           const bf16* zp = Z + (rowbase + (ok ? sx : 0)) * ZP + c0;
;           pv[j] = ok ? ld16(zp + 256) : (v4u){0u, 0u, 0u, 0u}; gv[j] = ok ? ld16(zp + 512) : (v4u){0u, 0u, 0u, 0u}; }
; #pragma unroll
;       for (int j = 0; j < 8; ++j) { const int r = 8 * j + rr, sx = t0 - 30 + r; float p[8], gt[8]; unpack8(pv[j], p); unpack8(gv[j], gt);
; #pragma unroll
;           for (int i = 0; i < 8; ++i) p[i] = p[i] * sigm(gt[i]);
;           if (r < 62) { *(LAS f32x4*)(gL + r * 64 + cg * 8) = (f32x4){p[0], p[1], p[2], p[3]}; *(LAS f32x4*)(gL + r * 64 + cg * 8 + 4) = (f32x4){p[4], p[5], p[6], p[7]}; }
;           if (last && sx >= SEQ - 30 && r < 62) { float* np = newc + ((size_t)seq * 30 + (sx - (SEQ - 30))) * GW + c0; *(f32x4*)np = (f32x4){p[0], p[1], p[2], p[3]}; *(f32x4*)(np + 4) = (f32x4){p[4], p[5], p[6], p[7]}; } }
.LBB0_377:
	s_or_b64 exec, exec, s[22:23]
	s_waitcnt vmcnt(14)
	v_lshlrev_b32_e32 v67, 16, v60
	v_and_b32_e32 v70, 0xffff0000, v60
	v_lshl_add_u32 v69, v73, 2, s69
	v_lshlrev_b32_e32 v71, 16, v61
	v_and_b32_e32 v73, 0xffff0000, v61
	v_mul_f32_e32 v60, 0xbfb8aa3b, v67
	v_mul_f32_e32 v61, 0xbfb8aa3b, v70
	v_exp_f32_e32 v60, v60
	v_exp_f32_e32 v61, v61
	v_lshlrev_b32_e32 v119, 16, v62
	v_and_b32_e32 v120, 0xffff0000, v62
	v_lshlrev_b32_e32 v121, 16, v63
	v_and_b32_e32 v122, 0xffff0000, v63
	v_lshlrev_b32_e32 v62, 16, v56
	v_and_b32_e32 v63, 0xffff0000, v56
	v_mul_f32_e32 v56, 0xbfb8aa3b, v71
	v_add_f32_e32 v60, 1.0, v60
	v_add_f32_e32 v61, 1.0, v61
	v_exp_f32_e32 v56, v56
	v_rcp_f32_e32 v60, v60
	v_rcp_f32_e32 v61, v61
	v_lshlrev_b32_e32 v70, 16, v58
	v_add_f32_e32 v56, 1.0, v56
	v_and_b32_e32 v71, 0xffff0000, v58
	v_pk_mul_f32 v[60:61], v[60:61], v[62:63]
	v_rcp_f32_e32 v62, v56
	v_mul_f32_e32 v56, 0xbfb8aa3b, v73
	v_exp_f32_e32 v56, v56
	v_mul_f32_e32 v58, 0xbfb8aa3b, v121
	v_exp_f32_e32 v58, v58
	v_lshl_add_u32 v67, v86, 8, v69
	v_add_f32_e32 v56, 1.0, v56
	v_rcp_f32_e32 v63, v56
	v_lshlrev_b32_e32 v56, 16, v57
	v_and_b32_e32 v57, 0xffff0000, v57
	v_add_f32_e32 v58, 1.0, v58
	v_pk_mul_f32 v[62:63], v[62:63], v[56:57]
	v_mul_f32_e32 v56, 0xbfb8aa3b, v119
	v_mul_f32_e32 v57, 0xbfb8aa3b, v120
	v_exp_f32_e32 v56, v56
	v_exp_f32_e32 v57, v57
	v_add_f32_e32 v56, 1.0, v56
	v_add_f32_e32 v57, 1.0, v57
	v_rcp_f32_e32 v56, v56
	v_rcp_f32_e32 v57, v57
	s_nop 0
	v_pk_mul_f32 v[56:57], v[56:57], v[70:71]
	v_rcp_f32_e32 v70, v58
	v_mul_f32_e32 v58, 0xbfb8aa3b, v122
	v_exp_f32_e32 v58, v58
	s_nop 0
	v_add_f32_e32 v58, 1.0, v58
	v_rcp_f32_e32 v71, v58
	v_lshlrev_b32_e32 v58, 16, v59
	v_and_b32_e32 v59, 0xffff0000, v59
	v_pk_mul_f32 v[58:59], v[70:71], v[58:59]
	s_and_saveexec_b64 s[22:23], s[18:19]
	s_cbranch_execz .LBB0_379
	ds_write_b128 v67, v[60:63]
	ds_write_b128 v67, v[56:59] offset:16

; #define LAS __attribute__((address_space(3)))
; __device__ __forceinline__ float sigm(float x) { return __builtin_amdgcn_rcpf(1.f + __builtin_amdgcn_exp2f(-1.44269504f * x)); }
; __device__ __forceinline__ void conv_unit_p(const bf16* __restrict__ Z, bf16* __restrict__ CAT, float* __restrict__ newc, ...
;     ...
;       for (int j = 0; j < 8; ++j) { const int r = 8 * j + rr, sx = t0 - 30 + r; const bool ok = (sx >= 0 && r < 62);
;           const bf16* zp = Z + (rowbase + (ok ? sx : 0)) * ZP + c0;
;           pv[j] = ok ? ld16(zp + 256) : (v4u){0u, 0u, 0u, 0u}; gv[j] = ok ? ld16(zp + 512) : (v4u){0u, 0u, 0u, 0u}; }
; #pragma unroll
;       for (int j = 0; j < 8; ++j) { const int r = 8 * j + rr, sx = t0 - 30 + r; float p[8], gt[8]; unpack8(pv[j], p); unpack8(gv[j], gt);
; #pragma unroll
;           for (int i = 0; i < 8; ++i) p[i] = p[i] * sigm(gt[i]);
;           if (r < 62) { *(LAS f32x4*)(gL + r * 64 + cg * 8) = (f32x4){p[0], p[1], p[2], p[3]}; *(LAS f32x4*)(gL + r * 64 + cg * 8 + 4) = (f32x4){p[4], p[5], p[6], p[7]}; }
;           if (last && sx >= SEQ - 30 && r < 62) { float* np = newc + ((size_t)seq * 30 + (sx - (SEQ - 30))) * GW + c0; *(f32x4*)np = (f32x4){p[0], p[1], p[2], p[3]}; *(f32x4*)(np + 4) = (f32x4){p[4], p[5], p[6], p[7]}; } }
.LBB0_381:
	s_or_b64 exec, exec, s[18:19]
	s_waitcnt vmcnt(12)
	s_nop 0
	v_lshlrev_b32_e32 v56, 16, v52
	v_and_b32_e32 v57, 0xffff0000, v52
	v_lshlrev_b32_e32 v58, 16, v53
	v_and_b32_e32 v59, 0xffff0000, v53
	v_mul_f32_e32 v52, 0xbfb8aa3b, v56
	v_mul_f32_e32 v53, 0xbfb8aa3b, v57
	v_exp_f32_e32 v52, v52
	v_exp_f32_e32 v53, v53
	v_lshlrev_b32_e32 v60, 16, v54
	v_and_b32_e32 v61, 0xffff0000, v54
	v_lshlrev_b32_e32 v62, 16, v55
	v_and_b32_e32 v63, 0xffff0000, v55
	v_lshlrev_b32_e32 v54, 16, v44
	v_and_b32_e32 v55, 0xffff0000, v44
	v_mul_f32_e32 v44, 0xbfb8aa3b, v58
	v_add_f32_e32 v52, 1.0, v52
	v_add_f32_e32 v53, 1.0, v53
	v_exp_f32_e32 v44, v44
	v_rcp_f32_e32 v52, v52
	v_rcp_f32_e32 v53, v53
	v_lshlrev_b32_e32 v56, 16, v46
	v_add_f32_e32 v44, 1.0, v44
	v_and_b32_e32 v57, 0xffff0000, v46
	v_pk_mul_f32 v[52:53], v[52:53], v[54:55]
	v_rcp_f32_e32 v54, v44
	v_mul_f32_e32 v44, 0xbfb8aa3b, v59
	v_exp_f32_e32 v44, v44
	v_mul_f32_e32 v46, 0xbfb8aa3b, v62
	v_exp_f32_e32 v46, v46
	v_add_f32_e32 v44, 1.0, v44
	v_rcp_f32_e32 v55, v44
	v_lshlrev_b32_e32 v44, 16, v45
	v_and_b32_e32 v45, 0xffff0000, v45
	v_add_f32_e32 v46, 1.0, v46
	v_pk_mul_f32 v[54:55], v[54:55], v[44:45]
	v_mul_f32_e32 v44, 0xbfb8aa3b, v60
	v_mul_f32_e32 v45, 0xbfb8aa3b, v61
	v_exp_f32_e32 v44, v44
	v_exp_f32_e32 v45, v45
	v_add_f32_e32 v44, 1.0, v44
	v_add_f32_e32 v45, 1.0, v45
	v_rcp_f32_e32 v44, v44
	v_rcp_f32_e32 v45, v45
	s_nop 0
	v_pk_mul_f32 v[44:45], v[44:45], v[56:57]
	v_rcp_f32_e32 v56, v46
	v_mul_f32_e32 v46, 0xbfb8aa3b, v63
	v_exp_f32_e32 v46, v46
	s_nop 0
	v_add_f32_e32 v46, 1.0, v46
	v_rcp_f32_e32 v57, v46
	v_lshlrev_b32_e32 v46, 16, v47
	v_and_b32_e32 v47, 0xffff0000, v47
	v_pk_mul_f32 v[46:47], v[56:57], v[46:47]
	v_lshl_add_u32 v56, v85, 8, v69
	s_and_saveexec_b64 s[18:19], s[16:17]
	s_cbranch_execz .LBB0_383
	ds_write_b128 v56, v[52:55]
	ds_write_b128 v56, v[44:47] offset:16

; #define LAS __attribute__((address_space(3)))
; __device__ __forceinline__ float sigm(float x) { return __builtin_amdgcn_rcpf(1.f + __builtin_amdgcn_exp2f(-1.44269504f * x)); }
; __device__ __forceinline__ void conv_unit_p(const bf16* __restrict__ Z, bf16* __restrict__ CAT, float* __restrict__ newc, ...
;     ...
;       for (int j = 0; j < 8; ++j) { const int r = 8 * j + rr, sx = t0 - 30 + r; const bool ok = (sx >= 0 && r < 62);
;           const bf16* zp = Z + (rowbase + (ok ? sx : 0)) * ZP + c0;
;           pv[j] = ok ? ld16(zp + 256) : (v4u){0u, 0u, 0u, 0u}; gv[j] = ok ? ld16(zp + 512) : (v4u){0u, 0u, 0u, 0u}; }
; #pragma unroll
;       for (int j = 0; j < 8; ++j) { const int r = 8 * j + rr, sx = t0 - 30 + r; float p[8], gt[8]; unpack8(pv[j], p); unpack8(gv[j], gt);
; #pragma unroll
;           for (int i = 0; i < 8; ++i) p[i] = p[i] * sigm(gt[i]);
;           if (r < 62) { *(LAS f32x4*)(gL + r * 64 + cg * 8) = (f32x4){p[0], p[1], p[2], p[3]}; *(LAS f32x4*)(gL + r * 64 + cg * 8 + 4) = (f32x4){p[4], p[5], p[6], p[7]}; }
;           if (last && sx >= SEQ - 30 && r < 62) { float* np = newc + ((size_t)seq * 30 + (sx - (SEQ - 30))) * GW + c0; *(f32x4*)np = (f32x4){p[0], p[1], p[2], p[3]}; *(f32x4*)(np + 4) = (f32x4){p[4], p[5], p[6], p[7]}; } }
.LBB0_385:
	s_or_b64 exec, exec, s[16:17]
	s_waitcnt vmcnt(10)
	s_nop 0
	v_lshlrev_b32_e32 v44, 16, v48
	v_and_b32_e32 v45, 0xffff0000, v48
	v_mul_f32_e32 v44, 0xbfb8aa3b, v44
	v_mul_f32_e32 v45, 0xbfb8aa3b, v45
	v_exp_f32_e32 v44, v44
	v_exp_f32_e32 v45, v45
	v_lshlrev_b32_e32 v48, 16, v49
	v_lshlrev_b32_e32 v46, 16, v36
	v_and_b32_e32 v47, 0xffff0000, v36
	v_mul_f32_e32 v36, 0xbfb8aa3b, v48
	v_add_f32_e32 v44, 1.0, v44
	v_add_f32_e32 v45, 1.0, v45
	v_exp_f32_e32 v36, v36
	v_rcp_f32_e32 v44, v44
	v_rcp_f32_e32 v45, v45
	v_and_b32_e32 v49, 0xffff0000, v49
	v_add_f32_e32 v36, 1.0, v36
	v_lshlrev_b32_e32 v52, 16, v50
	v_pk_mul_f32 v[44:45], v[44:45], v[46:47]
	v_rcp_f32_e32 v46, v36
	v_mul_f32_e32 v36, 0xbfb8aa3b, v49
	v_exp_f32_e32 v36, v36
	v_and_b32_e32 v50, 0xffff0000, v50
	v_lshlrev_b32_e32 v53, 16, v51
	v_lshlrev_b32_e32 v48, 16, v38
	v_add_f32_e32 v36, 1.0, v36
	v_rcp_f32_e32 v47, v36
	v_lshlrev_b32_e32 v36, 16, v37
	v_and_b32_e32 v37, 0xffff0000, v37
	v_and_b32_e32 v49, 0xffff0000, v38
	v_pk_mul_f32 v[46:47], v[46:47], v[36:37]
	v_mul_f32_e32 v36, 0xbfb8aa3b, v52
	v_mul_f32_e32 v37, 0xbfb8aa3b, v50
	v_exp_f32_e32 v36, v36
	v_exp_f32_e32 v37, v37
	v_mul_f32_e32 v38, 0xbfb8aa3b, v53
	v_exp_f32_e32 v38, v38
	v_add_f32_e32 v36, 1.0, v36
	v_add_f32_e32 v37, 1.0, v37
	v_rcp_f32_e32 v36, v36
	v_rcp_f32_e32 v37, v37
	v_and_b32_e32 v51, 0xffff0000, v51
	v_add_f32_e32 v38, 1.0, v38
	v_pk_mul_f32 v[36:37], v[36:37], v[48:49]
	v_rcp_f32_e32 v48, v38
	v_mul_f32_e32 v38, 0xbfb8aa3b, v51
	v_exp_f32_e32 v38, v38
	s_nop 0
	v_add_f32_e32 v38, 1.0, v38
	v_rcp_f32_e32 v49, v38
	v_lshlrev_b32_e32 v38, 16, v39
	v_and_b32_e32 v39, 0xffff0000, v39
	v_pk_mul_f32 v[38:39], v[48:49], v[38:39]
	v_lshl_add_u32 v48, v83, 8, v69
	s_and_saveexec_b64 s[16:17], s[14:15]
	s_cbranch_execz .LBB0_387
	ds_write_b128 v48, v[44:47]
	ds_write_b128 v48, v[36:39] offset:16

; #define LAS __attribute__((address_space(3)))
; __device__ __forceinline__ float sigm(float x) { return __builtin_amdgcn_rcpf(1.f + __builtin_amdgcn_exp2f(-1.44269504f * x)); }
; __device__ __forceinline__ void conv_unit_p(const bf16* __restrict__ Z, bf16* __restrict__ CAT, float* __restrict__ newc, ...
;     ...
;       for (int j = 0; j < 8; ++j) { const int r = 8 * j + rr, sx = t0 - 30 + r; const bool ok = (sx >= 0 && r < 62);
;           const bf16* zp = Z + (rowbase + (ok ? sx : 0)) * ZP + c0;
;           pv[j] = ok ? ld16(zp + 256) : (v4u){0u, 0u, 0u, 0u}; gv[j] = ok ? ld16(zp + 512) : (v4u){0u, 0u, 0u, 0u}; }
; #pragma unroll
;       for (int j = 0; j < 8; ++j) { const int r = 8 * j + rr, sx = t0 - 30 + r; float p[8], gt[8]; unpack8(pv[j], p); unpack8(gv[j], gt);
; #pragma unroll
;           for (int i = 0; i < 8; ++i) p[i] = p[i] * sigm(gt[i]);
;           if (r < 62) { *(LAS f32x4*)(gL + r * 64 + cg * 8) = (f32x4){p[0], p[1], p[2], p[3]}; *(LAS f32x4*)(gL + r * 64 + cg * 8 + 4) = (f32x4){p[4], p[5], p[6], p[7]}; }
;           if (last && sx >= SEQ - 30 && r < 62) { float* np = newc + ((size_t)seq * 30 + (sx - (SEQ - 30))) * GW + c0; *(f32x4*)np = (f32x4){p[0], p[1], p[2], p[3]}; *(f32x4*)(np + 4) = (f32x4){p[4], p[5], p[6], p[7]}; } }
.LBB0_389:
	s_or_b64 exec, exec, s[14:15]
	s_waitcnt vmcnt(8)
	s_nop 0
	v_lshlrev_b32_e32 v36, 16, v40
	v_and_b32_e32 v37, 0xffff0000, v40
	v_mul_f32_e32 v36, 0xbfb8aa3b, v36
	v_mul_f32_e32 v37, 0xbfb8aa3b, v37
	v_exp_f32_e32 v36, v36
	v_exp_f32_e32 v37, v37
	v_lshlrev_b32_e32 v40, 16, v41
	v_lshlrev_b32_e32 v38, 16, v28
	v_and_b32_e32 v39, 0xffff0000, v28
	v_mul_f32_e32 v28, 0xbfb8aa3b, v40
	v_add_f32_e32 v36, 1.0, v36
	v_add_f32_e32 v37, 1.0, v37
	v_exp_f32_e32 v28, v28
	v_rcp_f32_e32 v36, v36
	v_rcp_f32_e32 v37, v37
	v_and_b32_e32 v41, 0xffff0000, v41
	v_add_f32_e32 v28, 1.0, v28
	v_lshlrev_b32_e32 v44, 16, v42
	v_pk_mul_f32 v[36:37], v[36:37], v[38:39]
	v_rcp_f32_e32 v38, v28
	v_mul_f32_e32 v28, 0xbfb8aa3b, v41
	v_exp_f32_e32 v28, v28
	v_and_b32_e32 v42, 0xffff0000, v42
	v_lshlrev_b32_e32 v45, 16, v43
	v_lshlrev_b32_e32 v40, 16, v30
	v_add_f32_e32 v28, 1.0, v28
	v_rcp_f32_e32 v39, v28
	v_lshlrev_b32_e32 v28, 16, v29
	v_and_b32_e32 v29, 0xffff0000, v29
	v_and_b32_e32 v41, 0xffff0000, v30
	v_pk_mul_f32 v[38:39], v[38:39], v[28:29]
	v_mul_f32_e32 v28, 0xbfb8aa3b, v44
	v_mul_f32_e32 v29, 0xbfb8aa3b, v42
	v_exp_f32_e32 v28, v28
	v_exp_f32_e32 v29, v29
	v_mul_f32_e32 v30, 0xbfb8aa3b, v45
	v_exp_f32_e32 v30, v30
	v_add_f32_e32 v28, 1.0, v28
	v_add_f32_e32 v29, 1.0, v29
	v_rcp_f32_e32 v28, v28
	v_rcp_f32_e32 v29, v29
	v_and_b32_e32 v43, 0xffff0000, v43
	v_add_f32_e32 v30, 1.0, v30
	v_pk_mul_f32 v[28:29], v[28:29], v[40:41]
	v_rcp_f32_e32 v40, v30
	v_mul_f32_e32 v30, 0xbfb8aa3b, v43
	v_exp_f32_e32 v30, v30
	s_nop 0
	v_add_f32_e32 v30, 1.0, v30
	v_rcp_f32_e32 v41, v30
	v_lshlrev_b32_e32 v30, 16, v31
	v_and_b32_e32 v31, 0xffff0000, v31
	v_pk_mul_f32 v[30:31], v[40:41], v[30:31]
	v_lshl_add_u32 v40, v81, 8, v69
	s_and_saveexec_b64 s[14:15], s[12:13]
	s_cbranch_execz .LBB0_391
	ds_write_b128 v40, v[36:39]
	ds_write_b128 v40, v[28:31] offset:16

; #define LAS __attribute__((address_space(3)))
; __device__ __forceinline__ float sigm(float x) { return __builtin_amdgcn_rcpf(1.f + __builtin_amdgcn_exp2f(-1.44269504f * x)); }
; __device__ __forceinline__ void conv_unit_p(const bf16* __restrict__ Z, bf16* __restrict__ CAT, float* __restrict__ newc, ...
;     ...
;       for (int j = 0; j < 8; ++j) { const int r = 8 * j + rr, sx = t0 - 30 + r; const bool ok = (sx >= 0 && r < 62);
;           const bf16* zp = Z + (rowbase + (ok ? sx : 0)) * ZP + c0;
;           pv[j] = ok ? ld16(zp + 256) : (v4u){0u, 0u, 0u, 0u}; gv[j] = ok ? ld16(zp + 512) : (v4u){0u, 0u, 0u, 0u}; }
; #pragma unroll
;       for (int j = 0; j < 8; ++j) { const int r = 8 * j + rr, sx = t0 - 30 + r; float p[8], gt[8]; unpack8(pv[j], p); unpack8(gv[j], gt);
; #pragma unroll
;           for (int i = 0; i < 8; ++i) p[i] = p[i] * sigm(gt[i]);
;           if (r < 62) { *(LAS f32x4*)(gL + r * 64 + cg * 8) = (f32x4){p[0], p[1], p[2], p[3]}; *(LAS f32x4*)(gL + r * 64 + cg * 8 + 4) = (f32x4){p[4], p[5], p[6], p[7]}; }
;           if (last && sx >= SEQ - 30 && r < 62) { float* np = newc + ((size_t)seq * 30 + (sx - (SEQ - 30))) * GW + c0; *(f32x4*)np = (f32x4){p[0], p[1], p[2], p[3]}; *(f32x4*)(np + 4) = (f32x4){p[4], p[5], p[6], p[7]}; } }
.LBB0_393:
	s_or_b64 exec, exec, s[12:13]
	s_waitcnt vmcnt(6)
	s_nop 0
	v_lshlrev_b32_e32 v28, 16, v32
	v_and_b32_e32 v29, 0xffff0000, v32
	v_mul_f32_e32 v28, 0xbfb8aa3b, v28
	v_mul_f32_e32 v29, 0xbfb8aa3b, v29
	v_exp_f32_e32 v28, v28
	v_exp_f32_e32 v29, v29
	v_lshlrev_b32_e32 v32, 16, v33
	v_lshlrev_b32_e32 v30, 16, v20
	v_and_b32_e32 v31, 0xffff0000, v20
	v_mul_f32_e32 v20, 0xbfb8aa3b, v32
	v_add_f32_e32 v28, 1.0, v28
	v_add_f32_e32 v29, 1.0, v29
	v_exp_f32_e32 v20, v20
	v_rcp_f32_e32 v28, v28
	v_rcp_f32_e32 v29, v29
	v_and_b32_e32 v33, 0xffff0000, v33
	v_add_f32_e32 v20, 1.0, v20
	v_lshlrev_b32_e32 v36, 16, v34
	v_pk_mul_f32 v[28:29], v[28:29], v[30:31]
	v_rcp_f32_e32 v30, v20
	v_mul_f32_e32 v20, 0xbfb8aa3b, v33
	v_exp_f32_e32 v20, v20
	v_and_b32_e32 v34, 0xffff0000, v34
	v_lshlrev_b32_e32 v37, 16, v35
	v_lshlrev_b32_e32 v32, 16, v22
	v_add_f32_e32 v20, 1.0, v20
	v_rcp_f32_e32 v31, v20
	v_lshlrev_b32_e32 v20, 16, v21
	v_and_b32_e32 v21, 0xffff0000, v21
	v_and_b32_e32 v33, 0xffff0000, v22
	v_pk_mul_f32 v[30:31], v[30:31], v[20:21]
	v_mul_f32_e32 v20, 0xbfb8aa3b, v36
	v_mul_f32_e32 v21, 0xbfb8aa3b, v34
	v_exp_f32_e32 v20, v20
	v_exp_f32_e32 v21, v21
	v_mul_f32_e32 v22, 0xbfb8aa3b, v37
	v_exp_f32_e32 v22, v22
	v_add_f32_e32 v20, 1.0, v20
	v_add_f32_e32 v21, 1.0, v21
	v_rcp_f32_e32 v20, v20
	v_rcp_f32_e32 v21, v21
	v_and_b32_e32 v35, 0xffff0000, v35
	v_add_f32_e32 v22, 1.0, v22
	v_pk_mul_f32 v[20:21], v[20:21], v[32:33]
	v_rcp_f32_e32 v32, v22
	v_mul_f32_e32 v22, 0xbfb8aa3b, v35
	v_exp_f32_e32 v22, v22
	s_nop 0
	v_add_f32_e32 v22, 1.0, v22
	v_rcp_f32_e32 v33, v22
	v_lshlrev_b32_e32 v22, 16, v23
	v_and_b32_e32 v23, 0xffff0000, v23
	v_pk_mul_f32 v[22:23], v[32:33], v[22:23]
	s_and_saveexec_b64 s[12:13], s[10:11]
	s_cbranch_execz .LBB0_395
	v_lshl_add_u32 v32, v79, 8, v69
	ds_write_b128 v32, v[28:31]
	ds_write_b128 v32, v[20:23] offset:16

; #define LAS __attribute__((address_space(3)))
; __device__ __forceinline__ float sigm(float x) { return __builtin_amdgcn_rcpf(1.f + __builtin_amdgcn_exp2f(-1.44269504f * x)); }
; __device__ __forceinline__ void conv_unit_p(const bf16* __restrict__ Z, bf16* __restrict__ CAT, float* __restrict__ newc, ...
;     ...
;       for (int j = 0; j < 8; ++j) { const int r = 8 * j + rr, sx = t0 - 30 + r; const bool ok = (sx >= 0 && r < 62);
;           const bf16* zp = Z + (rowbase + (ok ? sx : 0)) * ZP + c0;
;           pv[j] = ok ? ld16(zp + 256) : (v4u){0u, 0u, 0u, 0u}; gv[j] = ok ? ld16(zp + 512) : (v4u){0u, 0u, 0u, 0u}; }
; #pragma unroll
;       for (int j = 0; j < 8; ++j) { const int r = 8 * j + rr, sx = t0 - 30 + r; float p[8], gt[8]; unpack8(pv[j], p); unpack8(gv[j], gt);
; #pragma unroll
;           for (int i = 0; i < 8; ++i) p[i] = p[i] * sigm(gt[i]);
;           if (r < 62) { *(LAS f32x4*)(gL + r * 64 + cg * 8) = (f32x4){p[0], p[1], p[2], p[3]}; *(LAS f32x4*)(gL + r * 64 + cg * 8 + 4) = (f32x4){p[4], p[5], p[6], p[7]}; }
;           if (last && sx >= SEQ - 30 && r < 62) { float* np = newc + ((size_t)seq * 30 + (sx - (SEQ - 30))) * GW + c0; *(f32x4*)np = (f32x4){p[0], p[1], p[2], p[3]}; *(f32x4*)(np + 4) = (f32x4){p[4], p[5], p[6], p[7]}; } }
.LBB0_397:
	s_or_b64 exec, exec, s[10:11]
	s_waitcnt vmcnt(4)
	s_nop 0
	v_lshlrev_b32_e32 v20, 16, v24
	v_and_b32_e32 v21, 0xffff0000, v24
	v_mul_f32_e32 v20, 0xbfb8aa3b, v20
	v_mul_f32_e32 v21, 0xbfb8aa3b, v21
	v_exp_f32_e32 v20, v20
	v_exp_f32_e32 v21, v21
	v_lshlrev_b32_e32 v24, 16, v25
	v_lshlrev_b32_e32 v22, 16, v12
	v_and_b32_e32 v23, 0xffff0000, v12
	v_mul_f32_e32 v12, 0xbfb8aa3b, v24
	v_add_f32_e32 v20, 1.0, v20
	v_add_f32_e32 v21, 1.0, v21
	v_exp_f32_e32 v12, v12
	v_rcp_f32_e32 v20, v20
	v_rcp_f32_e32 v21, v21
	v_and_b32_e32 v25, 0xffff0000, v25
	v_add_f32_e32 v12, 1.0, v12
	v_lshlrev_b32_e32 v28, 16, v26
	v_pk_mul_f32 v[20:21], v[20:21], v[22:23]
	v_rcp_f32_e32 v22, v12
	v_mul_f32_e32 v12, 0xbfb8aa3b, v25
	v_exp_f32_e32 v12, v12
	v_and_b32_e32 v26, 0xffff0000, v26
	v_lshlrev_b32_e32 v29, 16, v27
	v_lshlrev_b32_e32 v24, 16, v14
	v_add_f32_e32 v12, 1.0, v12
	v_rcp_f32_e32 v23, v12
	v_lshlrev_b32_e32 v12, 16, v13
	v_and_b32_e32 v13, 0xffff0000, v13
	v_and_b32_e32 v25, 0xffff0000, v14
	v_pk_mul_f32 v[22:23], v[22:23], v[12:13]
	v_mul_f32_e32 v12, 0xbfb8aa3b, v28
	v_mul_f32_e32 v13, 0xbfb8aa3b, v26
	v_exp_f32_e32 v12, v12
	v_exp_f32_e32 v13, v13
	v_mul_f32_e32 v14, 0xbfb8aa3b, v29
	v_exp_f32_e32 v14, v14
	v_add_f32_e32 v12, 1.0, v12
	v_add_f32_e32 v13, 1.0, v13
	v_rcp_f32_e32 v12, v12
	v_rcp_f32_e32 v13, v13
	v_and_b32_e32 v27, 0xffff0000, v27
	v_add_f32_e32 v14, 1.0, v14
	v_pk_mul_f32 v[12:13], v[12:13], v[24:25]
	v_rcp_f32_e32 v24, v14
	v_mul_f32_e32 v14, 0xbfb8aa3b, v27
	v_exp_f32_e32 v14, v14
	s_nop 0
	v_add_f32_e32 v14, 1.0, v14
	v_rcp_f32_e32 v25, v14
	v_lshlrev_b32_e32 v14, 16, v15
	v_and_b32_e32 v15, 0xffff0000, v15
	v_pk_mul_f32 v[14:15], v[24:25], v[14:15]
	s_and_saveexec_b64 s[10:11], s[8:9]
	s_cbranch_execz .LBB0_399
	v_lshl_add_u32 v24, v77, 8, v69
	ds_write_b128 v24, v[20:23]
	ds_write_b128 v24, v[12:15] offset:16

; #define LAS __attribute__((address_space(3)))
; __device__ __forceinline__ float sigm(float x) { return __builtin_amdgcn_rcpf(1.f + __builtin_amdgcn_exp2f(-1.44269504f * x)); }
; __device__ __forceinline__ void conv_unit_p(const bf16* __restrict__ Z, bf16* __restrict__ CAT, float* __restrict__ newc, ...
;     ...
;       for (int j = 0; j < 8; ++j) { const int r = 8 * j + rr, sx = t0 - 30 + r; const bool ok = (sx >= 0 && r < 62);
;           const bf16* zp = Z + (rowbase + (ok ? sx : 0)) * ZP + c0;
;           pv[j] = ok ? ld16(zp + 256) : (v4u){0u, 0u, 0u, 0u}; gv[j] = ok ? ld16(zp + 512) : (v4u){0u, 0u, 0u, 0u}; }
; #pragma unroll
;       for (int j = 0; j < 8; ++j) { const int r = 8 * j + rr, sx = t0 - 30 + r; float p[8], gt[8]; unpack8(pv[j], p); unpack8(gv[j], gt);
; #pragma unroll
;           for (int i = 0; i < 8; ++i) p[i] = p[i] * sigm(gt[i]);
;           if (r < 62) { *(LAS f32x4*)(gL + r * 64 + cg * 8) = (f32x4){p[0], p[1], p[2], p[3]}; *(LAS f32x4*)(gL + r * 64 + cg * 8 + 4) = (f32x4){p[4], p[5], p[6], p[7]}; }
;           if (last && sx >= SEQ - 30 && r < 62) { float* np = newc + ((size_t)seq * 30 + (sx - (SEQ - 30))) * GW + c0; *(f32x4*)np = (f32x4){p[0], p[1], p[2], p[3]}; *(f32x4*)(np + 4) = (f32x4){p[4], p[5], p[6], p[7]}; } }
.LBB0_401:
	s_or_b64 exec, exec, s[8:9]
	s_waitcnt vmcnt(2)
	s_nop 0
	v_lshlrev_b32_e32 v12, 16, v16
	v_and_b32_e32 v13, 0xffff0000, v16
	v_mul_f32_e32 v12, 0xbfb8aa3b, v12
	v_mul_f32_e32 v13, 0xbfb8aa3b, v13
	v_exp_f32_e32 v12, v12
	v_exp_f32_e32 v13, v13
	v_lshlrev_b32_e32 v16, 16, v17
	v_lshlrev_b32_e32 v14, 16, v4
	v_and_b32_e32 v15, 0xffff0000, v4
	v_mul_f32_e32 v4, 0xbfb8aa3b, v16
	v_add_f32_e32 v12, 1.0, v12
	v_add_f32_e32 v13, 1.0, v13
	v_exp_f32_e32 v4, v4
	v_rcp_f32_e32 v12, v12
	v_rcp_f32_e32 v13, v13
	v_and_b32_e32 v17, 0xffff0000, v17
	v_add_f32_e32 v4, 1.0, v4
	v_lshlrev_b32_e32 v20, 16, v18
	v_pk_mul_f32 v[12:13], v[12:13], v[14:15]
	v_rcp_f32_e32 v14, v4
	v_mul_f32_e32 v4, 0xbfb8aa3b, v17
	v_exp_f32_e32 v4, v4
	v_and_b32_e32 v18, 0xffff0000, v18
	v_lshlrev_b32_e32 v21, 16, v19
	v_lshlrev_b32_e32 v16, 16, v6
	v_add_f32_e32 v4, 1.0, v4
	v_rcp_f32_e32 v15, v4
	v_lshlrev_b32_e32 v4, 16, v5
	v_and_b32_e32 v5, 0xffff0000, v5
	v_and_b32_e32 v17, 0xffff0000, v6
	v_pk_mul_f32 v[14:15], v[14:15], v[4:5]
	v_mul_f32_e32 v4, 0xbfb8aa3b, v20
	v_mul_f32_e32 v5, 0xbfb8aa3b, v18
	v_exp_f32_e32 v4, v4
	v_exp_f32_e32 v5, v5
	v_mul_f32_e32 v6, 0xbfb8aa3b, v21
	v_exp_f32_e32 v6, v6
	v_add_f32_e32 v4, 1.0, v4
	v_add_f32_e32 v5, 1.0, v5
	v_rcp_f32_e32 v4, v4
	v_rcp_f32_e32 v5, v5
	v_and_b32_e32 v19, 0xffff0000, v19
	v_add_f32_e32 v6, 1.0, v6
	v_pk_mul_f32 v[4:5], v[4:5], v[16:17]
	v_rcp_f32_e32 v16, v6
	v_mul_f32_e32 v6, 0xbfb8aa3b, v19
	v_exp_f32_e32 v6, v6
	s_nop 0
	v_add_f32_e32 v6, 1.0, v6
	v_rcp_f32_e32 v17, v6
	v_lshlrev_b32_e32 v6, 16, v7
	v_and_b32_e32 v7, 0xffff0000, v7
	v_pk_mul_f32 v[6:7], v[16:17], v[6:7]
	s_and_saveexec_b64 s[8:9], s[6:7]
	s_cbranch_execz .LBB0_403
	v_lshl_add_u32 v16, v75, 8, v69
	ds_write_b128 v16, v[12:15]
	ds_write_b128 v16, v[4:7] offset:16

; #define LAS __attribute__((address_space(3)))
; __device__ __forceinline__ float sigm(float x) { return __builtin_amdgcn_rcpf(1.f + __builtin_amdgcn_exp2f(-1.44269504f * x)); }
; __device__ __forceinline__ void conv_unit_p(const bf16* __restrict__ Z, bf16* __restrict__ CAT, float* __restrict__ newc, ...
;     ...
;       for (int j = 0; j < 8; ++j) { const int r = 8 * j + rr, sx = t0 - 30 + r; const bool ok = (sx >= 0 && r < 62);
;           const bf16* zp = Z + (rowbase + (ok ? sx : 0)) * ZP + c0;
;           pv[j] = ok ? ld16(zp + 256) : (v4u){0u, 0u, 0u, 0u}; gv[j] = ok ? ld16(zp + 512) : (v4u){0u, 0u, 0u, 0u}; }
; #pragma unroll
;       for (int j = 0; j < 8; ++j) { const int r = 8 * j + rr, sx = t0 - 30 + r; float p[8], gt[8]; unpack8(pv[j], p); unpack8(gv[j], gt);
; #pragma unroll
;           for (int i = 0; i < 8; ++i) p[i] = p[i] * sigm(gt[i]);
;           if (r < 62) { *(LAS f32x4*)(gL + r * 64 + cg * 8) = (f32x4){p[0], p[1], p[2], p[3]}; *(LAS f32x4*)(gL + r * 64 + cg * 8 + 4) = (f32x4){p[4], p[5], p[6], p[7]}; }
;           if (last && sx >= SEQ - 30 && r < 62) { float* np = newc + ((size_t)seq * 30 + (sx - (SEQ - 30))) * GW + c0; *(f32x4*)np = (f32x4){p[0], p[1], p[2], p[3]}; *(f32x4*)(np + 4) = (f32x4){p[4], p[5], p[6], p[7]}; } }
.LBB0_405:
	s_or_b64 exec, exec, s[6:7]
	s_waitcnt vmcnt(0)
	s_nop 0
	v_lshlrev_b32_e32 v4, 16, v8
	v_and_b32_e32 v5, 0xffff0000, v8
	v_mul_f32_e32 v4, 0xbfb8aa3b, v4
	v_mul_f32_e32 v5, 0xbfb8aa3b, v5
	v_exp_f32_e32 v4, v4
	v_exp_f32_e32 v5, v5
	v_lshlrev_b32_e32 v8, 16, v9
	v_lshlrev_b32_e32 v6, 16, v0
	v_and_b32_e32 v7, 0xffff0000, v0
	v_mul_f32_e32 v0, 0xbfb8aa3b, v8
	v_add_f32_e32 v4, 1.0, v4
	v_add_f32_e32 v5, 1.0, v5
	v_exp_f32_e32 v0, v0
	v_rcp_f32_e32 v4, v4
	v_rcp_f32_e32 v5, v5
	v_and_b32_e32 v9, 0xffff0000, v9
	v_add_f32_e32 v0, 1.0, v0
	v_lshlrev_b32_e32 v12, 16, v10
	v_pk_mul_f32 v[4:5], v[4:5], v[6:7]
	v_rcp_f32_e32 v6, v0
	v_mul_f32_e32 v0, 0xbfb8aa3b, v9
	v_exp_f32_e32 v0, v0
	v_and_b32_e32 v10, 0xffff0000, v10
	v_lshlrev_b32_e32 v13, 16, v11
	v_lshlrev_b32_e32 v8, 16, v2
	v_add_f32_e32 v0, 1.0, v0
	v_rcp_f32_e32 v7, v0
	v_lshlrev_b32_e32 v0, 16, v1
	v_and_b32_e32 v1, 0xffff0000, v1
	v_and_b32_e32 v9, 0xffff0000, v2
	v_pk_mul_f32 v[6:7], v[6:7], v[0:1]
	v_mul_f32_e32 v0, 0xbfb8aa3b, v12
	v_mul_f32_e32 v1, 0xbfb8aa3b, v10
	v_exp_f32_e32 v0, v0
	v_exp_f32_e32 v1, v1
	v_mul_f32_e32 v2, 0xbfb8aa3b, v13
	v_exp_f32_e32 v2, v2
	v_add_f32_e32 v0, 1.0, v0
	v_add_f32_e32 v1, 1.0, v1
	v_rcp_f32_e32 v0, v0
	v_rcp_f32_e32 v1, v1
	v_and_b32_e32 v11, 0xffff0000, v11
	v_add_f32_e32 v2, 1.0, v2
	v_pk_mul_f32 v[0:1], v[0:1], v[8:9]
	v_rcp_f32_e32 v8, v2
	v_mul_f32_e32 v2, 0xbfb8aa3b, v11
	v_exp_f32_e32 v2, v2
	s_nop 0
	v_add_f32_e32 v2, 1.0, v2
	v_rcp_f32_e32 v9, v2
	v_lshlrev_b32_e32 v2, 16, v3
	v_and_b32_e32 v3, 0xffff0000, v3
	v_pk_mul_f32 v[2:3], v[8:9], v[2:3]
	s_and_saveexec_b64 s[6:7], vcc
	s_cbranch_execz .LBB0_407
	v_lshl_add_u32 v8, v65, 8, v69
	ds_write_b128 v8, v[4:7]
	ds_write_b128 v8, v[0:3] offset:16
